# v_li + M1 epilogue quad-contiguous stores via ds_bpermute lane transpose (4 lanes = 64B of one row)
# speedup vs baseline: 1.0093x; 1.0047x over previous
.LBB0_958:
	v_and_b32_e32 v186, 3, v0
	v_bfe_u32 v187, v0, 2, 4
	v_lshl_or_b32 v186, v186, 4, v187
	v_lshlrev_b32_e32 v186, 2, v186
	v_and_or_b32 v146, v146, -16, v187
	v_and_or_b32 v142, v142, -16, v187
	v_and_or_b32 v158, v158, -16, v187
	v_and_b32_e32 v187, 3, v0
	v_lshlrev_b32_e32 v187, 3, v187
	v_bfi_b32 v187, 31, v187, v226
	v_pk_mul_f32 v[126:127], v[126:127], v[140:141] op_sel_hi:[1,0]
	v_lshl_or_b32 v2, s59, 8, v187
	v_pk_mul_f32 v[130:131], v[130:131], v[140:141] op_sel_hi:[1,0]
	v_pk_mul_f32 v[128:129], v[128:129], v[140:141] op_sel_hi:[1,0]
	v_max_f32_e32 v126, 0, v126
	v_ashrrev_i32_e32 v3, 31, v2
	v_lshlrev_b64 v[138:139], 13, v[146:147]
	v_pk_mul_f32 v[132:133], v[132:133], v[140:141] op_sel_hi:[1,0]
	v_mul_f32_e32 v141, v126, v126
	v_max_f32_e32 v126, 0, v131
	v_max_f32_e32 v127, 0, v127
	v_max_f32_e32 v128, 0, v128
	v_lshl_add_u64 v[138:139], s[4:5], 0, v[138:139]
	v_lshlrev_b64 v[2:3], 1, v[2:3]
	v_max_f32_e32 v130, 0, v130
	v_mul_f32_e32 v126, v126, v126
	v_mul_f32_e32 v131, v127, v127
	v_max_f32_e32 v127, 0, v132
	v_mul_f32_e32 v132, v128, v128
	v_max_f32_e32 v128, 0, v133
	v_max_f32_e32 v129, 0, v129
	v_pk_mul_f32 v[118:119], v[118:119], v[140:141] op_sel_hi:[1,0]
	v_lshl_add_u64 v[138:139], v[138:139], 0, v[2:3]
	v_mul_f32_e32 v130, v130, v130
	v_mul_f32_e32 v127, v127, v127
	v_mul_f32_e32 v128, v128, v128
	v_mul_f32_e32 v129, v129, v129
	v_cvt_pk_bf16_f32 v126, v130, v126
	v_pk_mul_f32 v[122:123], v[122:123], v[140:141] op_sel_hi:[1,0]
	v_pk_mul_f32 v[120:121], v[120:121], v[140:141] op_sel_hi:[1,0]
	v_max_f32_e32 v118, 0, v118
	v_cvt_pk_bf16_f32 v127, v127, v128
	v_cvt_pk_bf16_f32 v128, v141, v131
	v_cvt_pk_bf16_f32 v129, v132, v129
	ds_bpermute_b32 v176, v186, v126
	ds_bpermute_b32 v177, v186, v127
	ds_bpermute_b32 v178, v186, v128
	ds_bpermute_b32 v179, v186, v129
	v_pk_mul_f32 v[124:125], v[124:125], v[140:141] op_sel_hi:[1,0]
	v_max_f32_e32 v119, 0, v119
	v_mul_f32_e32 v126, v118, v118
	v_max_f32_e32 v118, 0, v123
	v_max_f32_e32 v120, 0, v120
	v_max_f32_e32 v122, 0, v122
	v_mul_f32_e32 v118, v118, v118
	v_mul_f32_e32 v123, v119, v119
	v_max_f32_e32 v119, 0, v124
	v_mul_f32_e32 v124, v120, v120
	v_max_f32_e32 v120, 0, v125
	v_max_f32_e32 v121, 0, v121
	v_mul_f32_e32 v122, v122, v122
	v_mul_f32_e32 v119, v119, v119
	v_mul_f32_e32 v120, v120, v120
	v_mul_f32_e32 v121, v121, v121
	v_cvt_pk_bf16_f32 v118, v122, v118
	v_cvt_pk_bf16_f32 v119, v119, v120
	v_cvt_pk_bf16_f32 v120, v126, v123
	v_cvt_pk_bf16_f32 v121, v124, v121
	ds_bpermute_b32 v180, v186, v118
	ds_bpermute_b32 v181, v186, v119
	ds_bpermute_b32 v182, v186, v120
	ds_bpermute_b32 v183, v186, v121
	v_mov_b64_e32 v[184:185], v[138:139]
	s_waitcnt lgkmcnt(4)
	global_store_dwordx4 v[184:185], v[176:179], off sc1
	v_pk_mul_f32 v[110:111], v[110:111], v[144:145] op_sel_hi:[1,0]
	v_pk_mul_f32 v[114:115], v[114:115], v[144:145] op_sel_hi:[1,0]
	v_or_b32_e32 v118, 16, v146
	v_ashrrev_i32_e32 v119, 31, v118
	v_pk_mul_f32 v[112:113], v[112:113], v[144:145] op_sel_hi:[1,0]
	v_max_f32_e32 v110, 0, v110
	v_lshlrev_b64 v[118:119], 13, v[118:119]
	v_pk_mul_f32 v[116:117], v[116:117], v[144:145] op_sel_hi:[1,0]
	v_mul_f32_e32 v120, v110, v110
	v_max_f32_e32 v110, 0, v115
	v_max_f32_e32 v111, 0, v111
	v_max_f32_e32 v112, 0, v112
	v_lshl_add_u64 v[118:119], s[4:5], 0, v[118:119]
	v_max_f32_e32 v114, 0, v114
	v_mul_f32_e32 v110, v110, v110
	v_mul_f32_e32 v115, v111, v111
	v_max_f32_e32 v111, 0, v116
	v_mul_f32_e32 v116, v112, v112
	v_max_f32_e32 v112, 0, v117
	v_max_f32_e32 v113, 0, v113
	v_pk_mul_f32 v[102:103], v[102:103], v[144:145] op_sel_hi:[1,0]
	v_lshl_add_u64 v[118:119], v[118:119], 0, v[2:3]
	v_mul_f32_e32 v114, v114, v114
	v_mul_f32_e32 v111, v111, v111
	v_mul_f32_e32 v112, v112, v112
	v_mul_f32_e32 v113, v113, v113
	v_cvt_pk_bf16_f32 v110, v114, v110
	v_pk_mul_f32 v[106:107], v[106:107], v[144:145] op_sel_hi:[1,0]
	v_pk_mul_f32 v[104:105], v[104:105], v[144:145] op_sel_hi:[1,0]
	v_max_f32_e32 v102, 0, v102
	v_cvt_pk_bf16_f32 v111, v111, v112
	v_cvt_pk_bf16_f32 v112, v120, v115
	v_cvt_pk_bf16_f32 v113, v116, v113
	s_waitcnt lgkmcnt(0)
	global_store_dwordx4 v[184:185], v[180:183], off offset:64 sc1
	ds_bpermute_b32 v176, v186, v110
	ds_bpermute_b32 v177, v186, v111
	ds_bpermute_b32 v178, v186, v112
	ds_bpermute_b32 v179, v186, v113
	v_pk_mul_f32 v[108:109], v[108:109], v[144:145] op_sel_hi:[1,0]
	v_max_f32_e32 v103, 0, v103
	v_mul_f32_e32 v110, v102, v102
	v_max_f32_e32 v102, 0, v107
	v_max_f32_e32 v104, 0, v104
	v_max_f32_e32 v106, 0, v106
	v_mul_f32_e32 v102, v102, v102
	v_mul_f32_e32 v107, v103, v103
	v_max_f32_e32 v103, 0, v108
	v_mul_f32_e32 v108, v104, v104
	v_max_f32_e32 v104, 0, v109
	v_max_f32_e32 v105, 0, v105
	v_mul_f32_e32 v106, v106, v106
	v_mul_f32_e32 v103, v103, v103
	v_mul_f32_e32 v104, v104, v104
	v_mul_f32_e32 v105, v105, v105
	v_cvt_pk_bf16_f32 v102, v106, v102
	v_cvt_pk_bf16_f32 v103, v103, v104
	v_cvt_pk_bf16_f32 v104, v110, v107
	v_cvt_pk_bf16_f32 v105, v108, v105
	ds_bpermute_b32 v180, v186, v102
	ds_bpermute_b32 v181, v186, v103
	ds_bpermute_b32 v182, v186, v104
	ds_bpermute_b32 v183, v186, v105
	v_mov_b64_e32 v[184:185], v[118:119]
	s_waitcnt lgkmcnt(4)
	global_store_dwordx4 v[184:185], v[176:179], off sc1
	v_pk_mul_f32 v[94:95], v[94:95], v[148:149] op_sel_hi:[1,0]
	v_pk_mul_f32 v[98:99], v[98:99], v[148:149] op_sel_hi:[1,0]
	v_or_b32_e32 v102, 32, v146
	v_ashrrev_i32_e32 v103, 31, v102
	v_pk_mul_f32 v[96:97], v[96:97], v[148:149] op_sel_hi:[1,0]
	v_max_f32_e32 v94, 0, v94
	v_lshlrev_b64 v[102:103], 13, v[102:103]
	v_pk_mul_f32 v[100:101], v[100:101], v[148:149] op_sel_hi:[1,0]
	v_mul_f32_e32 v104, v94, v94
	v_max_f32_e32 v94, 0, v99
	v_max_f32_e32 v95, 0, v95
	v_max_f32_e32 v96, 0, v96
	v_lshl_add_u64 v[102:103], s[4:5], 0, v[102:103]
	v_max_f32_e32 v98, 0, v98
	v_mul_f32_e32 v94, v94, v94
	v_mul_f32_e32 v99, v95, v95
	v_max_f32_e32 v95, 0, v100
	v_mul_f32_e32 v100, v96, v96
	v_max_f32_e32 v96, 0, v101
	v_max_f32_e32 v97, 0, v97
	v_pk_mul_f32 v[86:87], v[86:87], v[148:149] op_sel_hi:[1,0]
	v_lshl_add_u64 v[102:103], v[102:103], 0, v[2:3]
	v_mul_f32_e32 v98, v98, v98
	v_mul_f32_e32 v95, v95, v95
	v_mul_f32_e32 v96, v96, v96
	v_mul_f32_e32 v97, v97, v97
	v_cvt_pk_bf16_f32 v94, v98, v94
	v_pk_mul_f32 v[90:91], v[90:91], v[148:149] op_sel_hi:[1,0]
	v_pk_mul_f32 v[88:89], v[88:89], v[148:149] op_sel_hi:[1,0]
	v_max_f32_e32 v86, 0, v86
	v_cvt_pk_bf16_f32 v95, v95, v96
	v_cvt_pk_bf16_f32 v96, v104, v99
	v_cvt_pk_bf16_f32 v97, v100, v97
	s_waitcnt lgkmcnt(0)
	global_store_dwordx4 v[184:185], v[180:183], off offset:64 sc1
	ds_bpermute_b32 v176, v186, v94
	ds_bpermute_b32 v177, v186, v95
	ds_bpermute_b32 v178, v186, v96
	ds_bpermute_b32 v179, v186, v97
	v_pk_mul_f32 v[92:93], v[92:93], v[148:149] op_sel_hi:[1,0]
	v_max_f32_e32 v87, 0, v87
	v_mul_f32_e32 v94, v86, v86
	v_max_f32_e32 v86, 0, v91
	v_max_f32_e32 v88, 0, v88
	v_max_f32_e32 v90, 0, v90
	v_mul_f32_e32 v86, v86, v86
	v_mul_f32_e32 v91, v87, v87
	v_max_f32_e32 v87, 0, v92
	v_mul_f32_e32 v92, v88, v88
	v_max_f32_e32 v88, 0, v93
	v_max_f32_e32 v89, 0, v89
	v_mul_f32_e32 v90, v90, v90
	v_mul_f32_e32 v87, v87, v87
	v_mul_f32_e32 v88, v88, v88
	v_mul_f32_e32 v89, v89, v89
	v_cvt_pk_bf16_f32 v86, v90, v86
	v_cvt_pk_bf16_f32 v87, v87, v88
	v_cvt_pk_bf16_f32 v88, v94, v91
	v_cvt_pk_bf16_f32 v89, v92, v89
	ds_bpermute_b32 v180, v186, v86
	ds_bpermute_b32 v181, v186, v87
	ds_bpermute_b32 v182, v186, v88
	ds_bpermute_b32 v183, v186, v89
	v_mov_b64_e32 v[184:185], v[102:103]
	s_waitcnt lgkmcnt(4)
	global_store_dwordx4 v[184:185], v[176:179], off sc1
	v_pk_mul_f32 v[78:79], v[78:79], v[150:151] op_sel_hi:[1,0]
	v_pk_mul_f32 v[82:83], v[82:83], v[150:151] op_sel_hi:[1,0]
	v_or_b32_e32 v86, 48, v146
	v_ashrrev_i32_e32 v87, 31, v86
	v_pk_mul_f32 v[80:81], v[80:81], v[150:151] op_sel_hi:[1,0]
	v_max_f32_e32 v78, 0, v78
	v_lshlrev_b64 v[86:87], 13, v[86:87]
	v_pk_mul_f32 v[84:85], v[84:85], v[150:151] op_sel_hi:[1,0]
	v_mul_f32_e32 v88, v78, v78
	v_max_f32_e32 v78, 0, v83
	v_max_f32_e32 v79, 0, v79
	v_max_f32_e32 v80, 0, v80
	v_lshl_add_u64 v[86:87], s[4:5], 0, v[86:87]
	v_max_f32_e32 v82, 0, v82
	v_mul_f32_e32 v78, v78, v78
	v_mul_f32_e32 v83, v79, v79
	v_max_f32_e32 v79, 0, v84
	v_mul_f32_e32 v84, v80, v80
	v_max_f32_e32 v80, 0, v85
	v_max_f32_e32 v81, 0, v81
	v_pk_mul_f32 v[72:73], v[72:73], v[150:151] op_sel_hi:[1,0]
	v_pk_mul_f32 v[70:71], v[70:71], v[150:151] op_sel_hi:[1,0]
	v_lshl_add_u64 v[86:87], v[86:87], 0, v[2:3]
	v_mul_f32_e32 v82, v82, v82
	v_mul_f32_e32 v79, v79, v79
	v_mul_f32_e32 v80, v80, v80
	v_mul_f32_e32 v81, v81, v81
	v_cvt_pk_bf16_f32 v78, v82, v78
	v_pk_mul_f32 v[76:77], v[76:77], v[150:151] op_sel_hi:[1,0]
	v_pk_mul_f32 v[74:75], v[74:75], v[150:151] op_sel_hi:[1,0]
	v_max_f32_e32 v70, 0, v70
	v_max_f32_e32 v71, 0, v71
	v_max_f32_e32 v72, 0, v72
	v_cvt_pk_bf16_f32 v79, v79, v80
	v_cvt_pk_bf16_f32 v80, v88, v83
	v_cvt_pk_bf16_f32 v81, v84, v81
	s_waitcnt lgkmcnt(0)
	global_store_dwordx4 v[184:185], v[180:183], off offset:64 sc1
	ds_bpermute_b32 v176, v186, v78
	ds_bpermute_b32 v177, v186, v79
	ds_bpermute_b32 v178, v186, v80
	ds_bpermute_b32 v179, v186, v81
	v_max_f32_e32 v74, 0, v74
	v_max_f32_e32 v73, 0, v73
	v_mul_f32_e32 v78, v70, v70
	v_max_f32_e32 v70, 0, v75
	v_mul_f32_e32 v75, v71, v71
	v_max_f32_e32 v71, 0, v76
	v_mul_f32_e32 v76, v72, v72
	v_max_f32_e32 v72, 0, v77
	v_mul_f32_e32 v70, v70, v70
	v_mul_f32_e32 v71, v71, v71
	v_mul_f32_e32 v72, v72, v72
	v_pk_mul_f32 v[62:63], v[62:63], v[136:137] op_sel_hi:[1,0]
	v_mul_f32_e32 v74, v74, v74
	v_mul_f32_e32 v73, v73, v73
	v_cvt_pk_bf16_f32 v70, v74, v70
	v_cvt_pk_bf16_f32 v71, v71, v72
	v_cvt_pk_bf16_f32 v72, v78, v75
	v_pk_mul_f32 v[66:67], v[66:67], v[136:137] op_sel_hi:[1,0]
	v_pk_mul_f32 v[64:65], v[64:65], v[136:137] op_sel_hi:[1,0]
	v_max_f32_e32 v62, 0, v62
	v_cvt_pk_bf16_f32 v73, v76, v73
	ds_bpermute_b32 v180, v186, v70
	ds_bpermute_b32 v181, v186, v71
	ds_bpermute_b32 v182, v186, v72
	ds_bpermute_b32 v183, v186, v73
	v_mov_b64_e32 v[184:185], v[86:87]
	s_waitcnt lgkmcnt(4)
	global_store_dwordx4 v[184:185], v[176:179], off sc1
	v_pk_mul_f32 v[68:69], v[68:69], v[136:137] op_sel_hi:[1,0]
	v_max_f32_e32 v63, 0, v63
	v_lshlrev_b64 v[70:71], 13, v[158:159]
	v_mul_f32_e32 v72, v62, v62
	v_max_f32_e32 v62, 0, v67
	v_max_f32_e32 v64, 0, v64
	v_lshl_add_u64 v[70:71], s[4:5], 0, v[70:71]
	v_max_f32_e32 v66, 0, v66
	v_mul_f32_e32 v62, v62, v62
	v_mul_f32_e32 v67, v63, v63
	v_max_f32_e32 v63, 0, v68
	v_mul_f32_e32 v68, v64, v64
	v_max_f32_e32 v64, 0, v69
	v_max_f32_e32 v65, 0, v65
	v_pk_mul_f32 v[54:55], v[54:55], v[136:137] op_sel_hi:[1,0]
	v_lshl_add_u64 v[70:71], v[70:71], 0, v[2:3]
	v_mul_f32_e32 v66, v66, v66
	v_mul_f32_e32 v63, v63, v63
	v_mul_f32_e32 v64, v64, v64
	v_mul_f32_e32 v65, v65, v65
	v_cvt_pk_bf16_f32 v62, v66, v62
	v_pk_mul_f32 v[60:61], v[60:61], v[136:137] op_sel_hi:[1,0]
	v_pk_mul_f32 v[58:59], v[58:59], v[136:137] op_sel_hi:[1,0]
	v_pk_mul_f32 v[56:57], v[56:57], v[136:137] op_sel_hi:[1,0]
	v_max_f32_e32 v54, 0, v54
	v_max_f32_e32 v55, 0, v55
	v_cvt_pk_bf16_f32 v63, v63, v64
	v_cvt_pk_bf16_f32 v64, v72, v67
	v_cvt_pk_bf16_f32 v65, v68, v65
	s_waitcnt lgkmcnt(0)
	global_store_dwordx4 v[184:185], v[180:183], off offset:64 sc1
	ds_bpermute_b32 v176, v186, v62
	ds_bpermute_b32 v177, v186, v63
	ds_bpermute_b32 v178, v186, v64
	ds_bpermute_b32 v179, v186, v65
	v_max_f32_e32 v56, 0, v56
	v_max_f32_e32 v58, 0, v58
	v_mul_f32_e32 v62, v54, v54
	v_max_f32_e32 v54, 0, v59
	v_mul_f32_e32 v59, v55, v55
	v_max_f32_e32 v55, 0, v60
	v_mul_f32_e32 v54, v54, v54
	v_mul_f32_e32 v55, v55, v55
	v_mul_f32_e32 v60, v56, v56
	v_max_f32_e32 v56, 0, v61
	v_max_f32_e32 v57, 0, v57
	v_mul_f32_e32 v58, v58, v58
	v_mul_f32_e32 v56, v56, v56
	v_mul_f32_e32 v57, v57, v57
	v_cvt_pk_bf16_f32 v54, v58, v54
	v_cvt_pk_bf16_f32 v55, v55, v56
	v_ashrrev_i32_e32 v143, 31, v142
	v_pk_mul_f32 v[46:47], v[46:47], v[136:137] op_sel:[0,1]
	v_cvt_pk_bf16_f32 v56, v62, v59
	v_cvt_pk_bf16_f32 v57, v60, v57
	ds_bpermute_b32 v180, v186, v54
	ds_bpermute_b32 v181, v186, v55
	ds_bpermute_b32 v182, v186, v56
	ds_bpermute_b32 v183, v186, v57
	v_mov_b64_e32 v[184:185], v[70:71]
	s_waitcnt lgkmcnt(4)
	global_store_dwordx4 v[184:185], v[176:179], off sc1
	v_pk_mul_f32 v[50:51], v[50:51], v[136:137] op_sel:[0,1]
	v_pk_mul_f32 v[48:49], v[48:49], v[136:137] op_sel:[0,1]
	v_lshlrev_b64 v[54:55], 13, v[142:143]
	v_max_f32_e32 v46, 0, v46
	v_lshl_add_u64 v[54:55], s[4:5], 0, v[54:55]
	v_pk_mul_f32 v[52:53], v[52:53], v[136:137] op_sel:[0,1]
	v_max_f32_e32 v50, 0, v50
	v_mul_f32_e32 v56, v46, v46
	v_max_f32_e32 v46, 0, v51
	v_max_f32_e32 v47, 0, v47
	v_max_f32_e32 v48, 0, v48
	v_lshl_add_u64 v[2:3], v[54:55], 0, v[2:3]
	v_mul_f32_e32 v50, v50, v50
	v_mul_f32_e32 v46, v46, v46
	v_mul_f32_e32 v51, v47, v47
	v_max_f32_e32 v47, 0, v52
	v_mul_f32_e32 v52, v48, v48
	v_max_f32_e32 v48, 0, v53
	s_mov_b32 s13, 0x20000
	v_mul_f32_e32 v47, v47, v47
	v_max_f32_e32 v49, 0, v49
	v_mul_f32_e32 v48, v48, v48
	v_cvt_pk_bf16_f32 v46, v50, v46
	v_add_co_u32_e32 v50, vcc, s13, v2
	v_pk_mul_f32 v[40:41], v[40:41], v[136:137] op_sel:[0,1]
	v_pk_mul_f32 v[38:39], v[38:39], v[136:137] op_sel:[0,1]
	v_mul_f32_e32 v49, v49, v49
	v_cvt_pk_bf16_f32 v47, v47, v48
	v_cvt_pk_bf16_f32 v48, v56, v51
	v_addc_co_u32_e32 v51, vcc, 0, v3, vcc
	v_pk_mul_f32 v[44:45], v[44:45], v[136:137] op_sel:[0,1]
	v_pk_mul_f32 v[42:43], v[42:43], v[136:137] op_sel:[0,1]
	v_max_f32_e32 v38, 0, v38
	v_max_f32_e32 v39, 0, v39
	v_max_f32_e32 v40, 0, v40
	v_cvt_pk_bf16_f32 v49, v52, v49
	s_waitcnt lgkmcnt(0)
	global_store_dwordx4 v[184:185], v[180:183], off offset:64 sc1
	ds_bpermute_b32 v176, v186, v46
	ds_bpermute_b32 v177, v186, v47
	ds_bpermute_b32 v178, v186, v48
	ds_bpermute_b32 v179, v186, v49
	s_mov_b64 s[22:23], 0x20000
	v_max_f32_e32 v41, 0, v41
	v_mul_f32_e32 v46, v38, v38
	v_max_f32_e32 v38, 0, v43
	v_mul_f32_e32 v43, v39, v39
	v_max_f32_e32 v39, 0, v44
	v_mul_f32_e32 v44, v40, v40
	v_max_f32_e32 v40, 0, v45
	v_mul_f32_e32 v39, v39, v39
	v_mul_f32_e32 v40, v40, v40
	v_pk_mul_f32 v[30:31], v[30:31], v[152:153] op_sel_hi:[1,0]
	v_lshl_add_u64 v[54:55], v[2:3], 0, s[22:23]
	v_max_f32_e32 v42, 0, v42
	v_mul_f32_e32 v38, v38, v38
	v_mul_f32_e32 v41, v41, v41
	v_cvt_pk_bf16_f32 v39, v39, v40
	v_cvt_pk_bf16_f32 v40, v46, v43
	v_pk_mul_f32 v[34:35], v[34:35], v[152:153] op_sel_hi:[1,0]
	v_pk_mul_f32 v[32:33], v[32:33], v[152:153] op_sel_hi:[1,0]
	v_max_f32_e32 v30, 0, v30
	v_mul_f32_e32 v42, v42, v42
	v_cvt_pk_bf16_f32 v38, v42, v38
	v_cvt_pk_bf16_f32 v41, v44, v41
	ds_bpermute_b32 v180, v186, v38
	ds_bpermute_b32 v181, v186, v39
	ds_bpermute_b32 v182, v186, v40
	ds_bpermute_b32 v183, v186, v41
	v_mov_b64_e32 v[184:185], v[50:51]
	s_waitcnt lgkmcnt(4)
	global_store_dwordx4 v[184:185], v[176:179], off sc1
	v_pk_mul_f32 v[36:37], v[36:37], v[152:153] op_sel_hi:[1,0]
	v_max_f32_e32 v34, 0, v34
	v_mul_f32_e32 v40, v30, v30
	v_max_f32_e32 v30, 0, v35
	v_max_f32_e32 v31, 0, v31
	v_max_f32_e32 v32, 0, v32
	v_mul_f32_e32 v34, v34, v34
	v_mul_f32_e32 v30, v30, v30
	v_mul_f32_e32 v35, v31, v31
	v_max_f32_e32 v31, 0, v36
	v_mul_f32_e32 v36, v32, v32
	v_max_f32_e32 v32, 0, v37
	v_mul_f32_e32 v31, v31, v31
	v_max_f32_e32 v33, 0, v33
	v_mul_f32_e32 v32, v32, v32
	v_cvt_pk_bf16_f32 v30, v34, v30
	v_add_co_u32_e32 v34, vcc, s72, v2
	v_pk_mul_f32 v[24:25], v[24:25], v[152:153] op_sel_hi:[1,0]
	v_pk_mul_f32 v[22:23], v[22:23], v[152:153] op_sel_hi:[1,0]
	v_mul_f32_e32 v33, v33, v33
	v_cvt_pk_bf16_f32 v31, v31, v32
	v_cvt_pk_bf16_f32 v32, v40, v35
	v_addc_co_u32_e32 v35, vcc, 0, v3, vcc
	v_pk_mul_f32 v[28:29], v[28:29], v[152:153] op_sel_hi:[1,0]
	v_pk_mul_f32 v[26:27], v[26:27], v[152:153] op_sel_hi:[1,0]
	v_max_f32_e32 v22, 0, v22
	v_max_f32_e32 v23, 0, v23
	v_max_f32_e32 v24, 0, v24
	v_cvt_pk_bf16_f32 v33, v36, v33
	s_waitcnt lgkmcnt(0)
	global_store_dwordx4 v[184:185], v[180:183], off offset:64 sc1
	ds_bpermute_b32 v176, v186, v30
	ds_bpermute_b32 v177, v186, v31
	ds_bpermute_b32 v178, v186, v32
	ds_bpermute_b32 v179, v186, v33
	s_mov_b64 s[22:23], 0x40000
	v_max_f32_e32 v26, 0, v26
	v_mul_f32_e32 v30, v22, v22
	v_max_f32_e32 v22, 0, v27
	v_mul_f32_e32 v27, v23, v23
	v_max_f32_e32 v23, 0, v28
	v_mul_f32_e32 v28, v24, v24
	v_max_f32_e32 v24, 0, v29
	v_mul_f32_e32 v22, v22, v22
	v_mul_f32_e32 v23, v23, v23
	v_max_f32_e32 v25, 0, v25
	v_mul_f32_e32 v24, v24, v24
	v_pk_mul_f32 v[16:17], v[16:17], v[154:155] op_sel_hi:[1,0]
	v_pk_mul_f32 v[14:15], v[14:15], v[154:155] op_sel_hi:[1,0]
	v_lshl_add_u64 v[38:39], v[2:3], 0, s[22:23]
	v_mul_f32_e32 v26, v26, v26
	v_mul_f32_e32 v25, v25, v25
	v_cvt_pk_bf16_f32 v22, v26, v22
	v_cvt_pk_bf16_f32 v23, v23, v24
	v_cvt_pk_bf16_f32 v24, v30, v27
	s_mov_b64 s[22:23], 0x60000
	v_pk_mul_f32 v[20:21], v[20:21], v[154:155] op_sel_hi:[1,0]
	v_pk_mul_f32 v[18:19], v[18:19], v[154:155] op_sel_hi:[1,0]
	v_max_f32_e32 v14, 0, v14
	v_max_f32_e32 v15, 0, v15
	v_max_f32_e32 v16, 0, v16
	s_mov_b32 s13, 0x60000
	v_cvt_pk_bf16_f32 v25, v28, v25
	ds_bpermute_b32 v180, v186, v22
	ds_bpermute_b32 v181, v186, v23
	ds_bpermute_b32 v182, v186, v24
	ds_bpermute_b32 v183, v186, v25
	v_mov_b64_e32 v[184:185], v[34:35]
	s_waitcnt lgkmcnt(4)
	global_store_dwordx4 v[184:185], v[176:179], off sc1
	v_max_f32_e32 v17, 0, v17
	v_pk_mul_f32 v[6:7], v[6:7], v[154:155] op_sel_hi:[1,0]
	v_lshl_add_u64 v[22:23], v[2:3], 0, s[22:23]
	v_mul_f32_e32 v24, v14, v14
	v_max_f32_e32 v14, 0, v19
	v_mul_f32_e32 v19, v15, v15
	v_max_f32_e32 v15, 0, v20
	v_mul_f32_e32 v20, v16, v16
	v_max_f32_e32 v16, 0, v21
	v_add_co_u32_e32 v2, vcc, s13, v2
	v_max_f32_e32 v18, 0, v18
	v_mul_f32_e32 v14, v14, v14
	v_mul_f32_e32 v15, v15, v15
	v_mul_f32_e32 v16, v16, v16
	v_mul_f32_e32 v17, v17, v17
	v_addc_co_u32_e32 v3, vcc, 0, v3, vcc
	v_pk_mul_f32 v[10:11], v[10:11], v[154:155] op_sel_hi:[1,0]
	v_pk_mul_f32 v[8:9], v[8:9], v[154:155] op_sel_hi:[1,0]
	v_max_f32_e32 v6, 0, v6
	v_max_f32_e32 v7, 0, v7
	v_mul_f32_e32 v18, v18, v18
	v_cvt_pk_bf16_f32 v14, v18, v14
	v_cvt_pk_bf16_f32 v15, v15, v16
	v_cvt_pk_bf16_f32 v16, v24, v19
	v_cvt_pk_bf16_f32 v17, v20, v17
	s_waitcnt lgkmcnt(0)
	global_store_dwordx4 v[184:185], v[180:183], off offset:64 sc1
	ds_bpermute_b32 v176, v186, v14
	ds_bpermute_b32 v177, v186, v15
	ds_bpermute_b32 v178, v186, v16
	ds_bpermute_b32 v179, v186, v17
	v_mov_b64_e32 v[188:189], v[2:3]
	v_pk_mul_f32 v[2:3], v[12:13], v[154:155] op_sel_hi:[1,0]
	v_mul_f32_e32 v12, v6, v6
	v_max_f32_e32 v6, 0, v11
	v_mul_f32_e32 v11, v7, v7
	v_max_f32_e32 v7, 0, v8
	v_mul_f32_e32 v13, v7, v7
	v_max_f32_e32 v7, 0, v9
	v_max_f32_e32 v10, 0, v10
	v_mul_f32_e32 v6, v6, v6
	v_max_f32_e32 v2, 0, v2
	v_max_f32_e32 v3, 0, v3
	v_mul_f32_e32 v9, v7, v7
	v_mul_f32_e32 v10, v10, v10
	v_mul_f32_e32 v2, v2, v2
	v_mul_f32_e32 v3, v3, v3
	v_cvt_pk_bf16_f32 v6, v10, v6
	v_cvt_pk_bf16_f32 v7, v2, v3
	v_cvt_pk_bf16_f32 v8, v12, v11
	v_cvt_pk_bf16_f32 v9, v13, v9
	ds_bpermute_b32 v180, v186, v6
	ds_bpermute_b32 v181, v186, v7
	ds_bpermute_b32 v182, v186, v8
	ds_bpermute_b32 v183, v186, v9
	v_mov_b64_e32 v[184:185], v[188:189]
	s_waitcnt lgkmcnt(4)
	global_store_dwordx4 v[184:185], v[176:179], off sc1
	s_waitcnt lgkmcnt(0)
	global_store_dwordx4 v[184:185], v[180:183], off offset:64 sc1
	s_andn2_b64 vcc, exec, s[20:21]
	s_mov_b64 s[20:21], -1
	s_cbranch_vccnz .LBB0_936
	s_andn2_b64 vcc, exec, s[2:3]
	s_cbranch_vccnz .LBB0_935
	s_barrier
	s_branch .LBB0_935
